# v50: v40 + scan: state-update LDS reads hoisted into the O-block tail (8-9 early, 2-3 late; decay scaling replaces s_nop), context steps keep a standalone head
# baseline (speedup 1.0000x reference)
; #define LAS __attribute__((address_space(3)))
; __device__ __forceinline__ void p3_gla_scan(LAS unsigned char* lds_, const Params& p) {
;     ...
;             { const f32x4 eb = *(const LAS f32x4*)(buf + BL_EBL + (16 * w + 4 * lq) * 4);
;               const bf16x8 ka0 = ldfrag(buf + BL_KH, 16 * w + l15, S64, (8 * lq) * 2), ka1 = ldfrag(buf + BL_KH, 16 * w + l15, S64, (8 * lq + 32) * 2);
; #pragma unroll
;               for (int tv = 0; tv < 4; ++tv) { S[tv] = S[tv] * eb;
.LBB0_618:
	ds_read_b128 v[138:141], v129 offset:45056
	ds_read_b128 v[134:137], v119 offset:17408
	ds_read_b128 v[142:145], v120 offset:46080
	ds_read_b128 v[146:149], v119 offset:17472
	ds_read_b128 v[150:153], v120 offset:46144
	ds_read_b128 v[170:173], v120 offset:48384
	ds_read_b128 v[174:177], v120 offset:48448
	ds_read_b128 v[178:181], v120 offset:50688
	ds_read_b128 v[182:185], v120 offset:50752
	ds_read_b128 v[186:189], v120 offset:52992
	ds_read_b128 v[190:193], v120 offset:53056
	s_add_i32 s34, s30, -3
	s_waitcnt lgkmcnt(10)
	v_pk_mul_f32 v[78:79], v[78:79], v[138:139]
	v_pk_mul_f32 v[80:81], v[80:81], v[140:141]
	v_pk_mul_f32 v[74:75], v[74:75], v[138:139]
	v_pk_mul_f32 v[76:77], v[76:77], v[140:141]
	v_pk_mul_f32 v[70:71], v[70:71], v[138:139]
	v_pk_mul_f32 v[72:73], v[72:73], v[140:141]
	v_mul_f32_e64 v66, v66, v138
	v_mul_f32_e64 v67, v67, v139
	v_pk_mul_f32 v[68:69], v[68:69], v[140:141]
	s_branch .Lmy_se_tail

; #define LAS __attribute__((address_space(3)))
; __device__ __forceinline__ unsigned pk2(float lo, float hi) { const f32x2 v = {lo, hi}; return __builtin_bit_cast(unsigned, __builtin_convertvector(v, bf16x2_hw)); }
; __device__ __forceinline__ void p3_gla_scan(LAS unsigned char* lds_, const Params& p) {
;     ...
;               for (int tv = 0; tv < 4; ++tv) { S[tv] = S[tv] * eb;
;                   S[tv] = __builtin_amdgcn_mfma_f32_16x16x32_bf16(ka0, ldfrag(vt, 16 * tv + l15, S64, (8 * lq) * 2), S[tv], 0, 0, 0);
;                   S[tv] = __builtin_amdgcn_mfma_f32_16x16x32_bf16(ka1, ldfrag(vt, 16 * tv + l15, S64, (8 * lq + 32) * 2), S[tv], 0, 0, 0);
;                   *(LAS v2u*)(stn + (16 * tv + l15) * S128 + (16 * w + 4 * lq) * 2) = (v2u){pk2(S[tv][0], S[tv][1]), pk2(S[tv][2], S[tv][3])}; } }
.Lmy_so_tail:
	s_waitcnt lgkmcnt(8)
	v_mfma_f32_16x16x32_bf16 v[78:81], v[132:135], v[140:143], v[78:81]
	s_waitcnt lgkmcnt(6)
	v_mfma_f32_16x16x32_bf16 v[78:81], v[144:147], v[170:173], v[78:81]
	s_waitcnt lgkmcnt(5)
	v_mfma_f32_16x16x32_bf16 v[74:77], v[132:135], v[174:177], v[74:77]
	s_waitcnt lgkmcnt(4)
	v_mfma_f32_16x16x32_bf16 v[74:77], v[144:147], v[178:181], v[74:77]
	s_waitcnt lgkmcnt(3)
	v_mfma_f32_16x16x32_bf16 v[70:73], v[132:135], v[182:185], v[70:73]
	s_waitcnt lgkmcnt(2)
	v_mfma_f32_16x16x32_bf16 v[70:73], v[144:147], v[186:189], v[70:73]
	s_waitcnt lgkmcnt(1)
	v_mfma_f32_16x16x32_bf16 v[66:69], v[132:135], v[190:193], v[66:69]
	s_waitcnt lgkmcnt(0)
	v_mfma_f32_16x16x32_bf16 v[66:69], v[144:147], v[194:197], v[66:69]
	v_cvt_pk_bf16_f32 v198, v78, v79
	v_cvt_pk_bf16_f32 v199, v80, v81
	ds_write_b64 v130, v[198:199]
	v_cvt_pk_bf16_f32 v200, v74, v75
	v_cvt_pk_bf16_f32 v201, v76, v77
	ds_write_b64 v130, v[200:201] offset:4352
	v_cvt_pk_bf16_f32 v202, v70, v71
	v_cvt_pk_bf16_f32 v203, v72, v73
	ds_write_b64 v130, v[202:203] offset:8704
	s_cmpk_gt_u32 s33, 0x41
	s_nop 0
	v_cvt_pk_bf16_f32 v204, v66, v67
	v_cvt_pk_bf16_f32 v205, v68, v69
	ds_write_b64 v130, v[204:205] offset:13056
	s_cbranch_scc1 .LBB0_596

; #define LAS __attribute__((address_space(3)))
; __device__ __forceinline__ unsigned pk2(float lo, float hi) { const f32x2 v = {lo, hi}; return __builtin_bit_cast(unsigned, __builtin_convertvector(v, bf16x2_hw)); }
; __device__ __forceinline__ void st_global_b64(void* p, v2u v) { asm volatile("global_store_dwordx2 %0, %1, off\n\ts_nop 1" :: "v"(p), "v"(v) : "memory"); }
; __device__ __forceinline__ void p3_gla_scan(LAS unsigned char* lds_, const Params& p) {
;     ...
;             if (!ctx) {
;                 const int ti = w & 3; const size_t row0 = (size_t)(b * SEQ + ch * 64);
; #pragma unroll
;                 for (int t2 = 0; t2 < 2; ++t2) { const int tv = 2 * (w >> 2) + t2; f32x4 o4 = (f32x4){0.f, 0.f, 0.f, 0.f};
; #pragma unroll
;                     for (int ks = 0; ks < 4; ++ks) o4 = __builtin_amdgcn_mfma_f32_16x16x32_bf16(ldfrag(stc, 16 * tv + l15, S128, (8 * lq + 32 * ks) * 2), ldfrag(buf + BL_QT, 16 * ti + l15, S128, (8 * lq + 32 * ks) * 2), o4, 0, 0, 0);
; #pragma unroll
;                     for (int ks = 0; ks < 2; ++ks) o4 = __builtin_amdgcn_mfma_f32_16x16x32_bf16(ldfrag(vt, 16 * tv + l15, S64, (8 * lq + 32 * ks) * 2), ldfrag(buf + BL_ATT, 16 * ti + l15, S64, (8 * lq + 32 * ks) * 2), o4, 0, 0, 0);
;                     const int i = 16 * ti + l15, v0 = 16 * tv + 4 * lq;
;                     st_global_b64(Og + (row0 + i) * VALW + h * DV + dvs * 64 + v0, (v2u){pk2(o4[0], o4[1]), pk2(o4[2], o4[3])}); }
;             }
;             { const f32x4 eb = *(const LAS f32x4*)(buf + BL_EBL + (16 * w + 4 * lq) * 4);
;               const bf16x8 ka0 = ldfrag(buf + BL_KH, 16 * w + l15, S64, (8 * lq) * 2), ka1 = ldfrag(buf + BL_KH, 16 * w + l15, S64, (8 * lq + 32) * 2);
; #pragma unroll
;               for (int tv = 0; tv < 4; ++tv) { S[tv] = S[tv] * eb;
;                   S[tv] = __builtin_amdgcn_mfma_f32_16x16x32_bf16(ka0, ldfrag(vt, 16 * tv + l15, S64, (8 * lq) * 2), S[tv], 0, 0, 0);
;                   S[tv] = __builtin_amdgcn_mfma_f32_16x16x32_bf16(ka1, ldfrag(vt, 16 * tv + l15, S64, (8 * lq + 32) * 2), S[tv], 0, 0, 0);
;                   *(LAS v2u*)(stn + (16 * tv + l15) * S128 + (16 * w + 4 * lq) * 2) = (v2u){pk2(S[tv][0], S[tv][1]), pk2(S[tv][2], S[tv][3])}; } }
.LBB0_616:
	s_cmp_gt_u32 s33, 3
	s_cselect_b64 s[16:17], -1, 0
	s_cmp_lt_u32 s33, 4
	v_add_u32_e32 v132, v111, v105
	s_cbranch_scc1 .LBB0_618
	ds_read_b128 v[134:137], v115
	ds_read_b128 v[150:153], v132
	ds_read_b128 v[170:173], v117
	ds_read_b128 v[138:141], v115 offset:64
	ds_read_b128 v[154:157], v132 offset:64
	ds_read_b128 v[174:177], v117 offset:64
	ds_read_b128 v[142:145], v115 offset:128
	ds_read_b128 v[158:161], v132 offset:128
	ds_read_b128 v[178:181], v117 offset:128
	ds_read_b128 v[146:149], v115 offset:192
	ds_read_b128 v[162:165], v132 offset:192
	ds_read_b128 v[182:185], v117 offset:192
	v_add_u32_e32 v133, v87, v105
	s_waitcnt lgkmcnt(10)
	v_mfma_f32_16x16x32_bf16 v[222:225], v[134:137], v[150:153], 0
	s_waitcnt lgkmcnt(9)
	v_mfma_f32_16x16x32_bf16 v[226:229], v[170:173], v[150:153], 0
	ds_read_b128 v[194:197], v133 offset:46080
	ds_read_b128 v[186:189], v116 offset:35840
	ds_read_b128 v[202:205], v118 offset:46080
	ds_read_b128 v[198:201], v133 offset:46144
	ds_read_b128 v[190:193], v116 offset:35904
	ds_read_b128 v[206:209], v118 offset:46144
	s_and_b64 s[18:19], s[12:13], exec
	s_cselect_b32 s18, s33, s31
	s_lshl_b32 s18, s18, 6
	s_add_i32 s18, s18, s8
	s_ashr_i32 s19, s18, 31
	v_or_b32_e32 v210, s18, v86
	v_mov_b32_e32 v211, s19
	v_lshlrev_b64 v[212:213], 12, v[210:211]
	v_lshl_add_u64 v[214:215], s[14:15], 0, v[212:213]
	v_lshl_add_u64 v[218:219], v[98:99], 1, v[214:215]
	v_lshl_add_u64 v[220:221], v[100:101], 1, v[214:215]
	v_lshl_add_u64 v[220:221], v[220:221], 0, 32
	s_waitcnt lgkmcnt(13)
	v_mfma_f32_16x16x32_bf16 v[222:225], v[138:141], v[154:157], v[222:225]
	s_waitcnt lgkmcnt(12)
	v_mfma_f32_16x16x32_bf16 v[226:229], v[174:177], v[154:157], v[226:229]
	s_waitcnt lgkmcnt(10)
	v_mfma_f32_16x16x32_bf16 v[222:225], v[142:145], v[158:161], v[222:225]
	s_waitcnt lgkmcnt(9)
	v_mfma_f32_16x16x32_bf16 v[226:229], v[178:181], v[158:161], v[226:229]
	s_waitcnt lgkmcnt(7)
	v_mfma_f32_16x16x32_bf16 v[222:225], v[146:149], v[162:165], v[222:225]
	s_waitcnt lgkmcnt(6)
	v_mfma_f32_16x16x32_bf16 v[226:229], v[182:185], v[162:165], v[226:229]
	ds_read_b128 v[138:141], v129 offset:45056
	ds_read_b128 v[134:137], v119 offset:17408
	ds_read_b128 v[142:145], v120 offset:46080
	ds_read_b128 v[146:149], v119 offset:17472
	ds_read_b128 v[150:153], v120 offset:46144
	ds_read_b128 v[170:173], v120 offset:48384
	ds_read_b128 v[174:177], v120 offset:48448
	ds_read_b128 v[178:181], v120 offset:50688
	ds_read_b128 v[182:185], v120 offset:50752
	s_waitcnt lgkmcnt(13)
	v_mfma_f32_16x16x32_bf16 v[222:225], v[194:197], v[186:189], v[222:225]
	s_waitcnt lgkmcnt(12)
	v_mfma_f32_16x16x32_bf16 v[226:229], v[202:205], v[186:189], v[226:229]
	s_waitcnt lgkmcnt(10)
	v_mfma_f32_16x16x32_bf16 v[222:225], v[198:201], v[190:193], v[222:225]
	s_waitcnt lgkmcnt(9)
	v_mfma_f32_16x16x32_bf16 v[226:229], v[206:209], v[190:193], v[226:229]
	ds_read_b128 v[186:189], v120 offset:52992
	ds_read_b128 v[190:193], v120 offset:53056
	s_add_i32 s34, s30, -3
	s_waitcnt lgkmcnt(10)
	v_pk_mul_f32 v[78:79], v[78:79], v[138:139]
	v_pk_mul_f32 v[80:81], v[80:81], v[140:141]
	v_pk_mul_f32 v[74:75], v[74:75], v[138:139]
	v_pk_mul_f32 v[76:77], v[76:77], v[140:141]
	v_pk_mul_f32 v[70:71], v[70:71], v[138:139]
	v_pk_mul_f32 v[72:73], v[72:73], v[140:141]
	v_mul_f32_e64 v66, v66, v138
	v_mul_f32_e64 v67, v67, v139
	v_pk_mul_f32 v[68:69], v[68:69], v[140:141]
	v_cvt_pk_bf16_f32 v230, v222, v223
	v_cvt_pk_bf16_f32 v231, v224, v225
	global_store_dwordx2 v[218:219], v[230:231], off
	s_nop 1
	v_cvt_pk_bf16_f32 v232, v226, v227
	v_cvt_pk_bf16_f32 v233, v228, v229
	global_store_dwordx2 v[220:221], v[232:233], off
	s_nop 1
.Lmy_se_tail:
	s_waitcnt lgkmcnt(8)
	v_mfma_f32_16x16x32_bf16 v[78:81], v[134:137], v[142:145], v[78:81]
	s_waitcnt lgkmcnt(6)
	v_mfma_f32_16x16x32_bf16 v[78:81], v[146:149], v[150:153], v[78:81]
	s_waitcnt lgkmcnt(5)
	v_mfma_f32_16x16x32_bf16 v[74:77], v[134:137], v[170:173], v[74:77]
	s_waitcnt lgkmcnt(4)
	v_mfma_f32_16x16x32_bf16 v[74:77], v[146:149], v[174:177], v[74:77]
	s_waitcnt lgkmcnt(3)
	v_mfma_f32_16x16x32_bf16 v[70:73], v[134:137], v[178:181], v[70:73]
	s_waitcnt lgkmcnt(2)
	v_mfma_f32_16x16x32_bf16 v[70:73], v[146:149], v[182:185], v[70:73]
	s_waitcnt lgkmcnt(1)
	v_mfma_f32_16x16x32_bf16 v[66:69], v[134:137], v[186:189], v[66:69]
	s_waitcnt lgkmcnt(0)
	v_mfma_f32_16x16x32_bf16 v[66:69], v[146:149], v[190:193], v[66:69]
	v_cvt_pk_bf16_f32 v194, v78, v79
	v_cvt_pk_bf16_f32 v195, v80, v81
	ds_write_b64 v130, v[194:195] offset:17408
	v_cvt_pk_bf16_f32 v196, v74, v75
	v_cvt_pk_bf16_f32 v197, v76, v77
	ds_write_b64 v130, v[196:197] offset:21760
	v_cvt_pk_bf16_f32 v198, v70, v71
	v_cvt_pk_bf16_f32 v199, v72, v73
	ds_write_b64 v130, v[198:199] offset:26112
	s_cmpk_gt_u32 s34, 0x42
	s_nop 0
	v_cvt_pk_bf16_f32 v200, v66, v67
	v_cvt_pk_bf16_f32 v201, v68, v69
	ds_write_b64 v130, v[200:201] offset:30464
	s_waitcnt lgkmcnt(0)
	s_barrier
	s_cbranch_scc0 .LBB0_621
	s_cmp_gt_u32 s34, 64
	s_cbranch_scc0 .LBB0_624

; #define LAS __attribute__((address_space(3)))
; __device__ __forceinline__ unsigned pk2(float lo, float hi) { const f32x2 v = {lo, hi}; return __builtin_bit_cast(unsigned, __builtin_convertvector(v, bf16x2_hw)); }
; __device__ __forceinline__ void st_global_b64(void* p, v2u v) { asm volatile("global_store_dwordx2 %0, %1, off\n\ts_nop 1" :: "v"(p), "v"(v) : "memory"); }
; __device__ __forceinline__ void p3_gla_scan(LAS unsigned char* lds_, const Params& p) {
;     ...
;             if (!ctx) {
;                 const int ti = w & 3; const size_t row0 = (size_t)(b * SEQ + ch * 64);
; #pragma unroll
;                 for (int t2 = 0; t2 < 2; ++t2) { const int tv = 2 * (w >> 2) + t2; f32x4 o4 = (f32x4){0.f, 0.f, 0.f, 0.f};
; #pragma unroll
;                     for (int ks = 0; ks < 4; ++ks) o4 = __builtin_amdgcn_mfma_f32_16x16x32_bf16(ldfrag(stc, 16 * tv + l15, S128, (8 * lq + 32 * ks) * 2), ldfrag(buf + BL_QT, 16 * ti + l15, S128, (8 * lq + 32 * ks) * 2), o4, 0, 0, 0);
; #pragma unroll
;                     for (int ks = 0; ks < 2; ++ks) o4 = __builtin_amdgcn_mfma_f32_16x16x32_bf16(ldfrag(vt, 16 * tv + l15, S64, (8 * lq + 32 * ks) * 2), ldfrag(buf + BL_ATT, 16 * ti + l15, S64, (8 * lq + 32 * ks) * 2), o4, 0, 0, 0);
;                     const int i = 16 * ti + l15, v0 = 16 * tv + 4 * lq;
;                     st_global_b64(Og + (row0 + i) * VALW + h * DV + dvs * 64 + v0, (v2u){pk2(o4[0], o4[1]), pk2(o4[2], o4[3])}); }
;             }
;             { const f32x4 eb = *(const LAS f32x4*)(buf + BL_EBL + (16 * w + 4 * lq) * 4);
;               const bf16x8 ka0 = ldfrag(buf + BL_KH, 16 * w + l15, S64, (8 * lq) * 2), ka1 = ldfrag(buf + BL_KH, 16 * w + l15, S64, (8 * lq + 32) * 2);
; #pragma unroll
;               for (int tv = 0; tv < 4; ++tv) { S[tv] = S[tv] * eb;
;                   S[tv] = __builtin_amdgcn_mfma_f32_16x16x32_bf16(ka0, ldfrag(vt, 16 * tv + l15, S64, (8 * lq) * 2), S[tv], 0, 0, 0);
;                   S[tv] = __builtin_amdgcn_mfma_f32_16x16x32_bf16(ka1, ldfrag(vt, 16 * tv + l15, S64, (8 * lq + 32) * 2), S[tv], 0, 0, 0);
;                   *(LAS v2u*)(stn + (16 * tv + l15) * S128 + (16 * w + 4 * lq) * 2) = (v2u){pk2(S[tv][0], S[tv][1]), pk2(S[tv][2], S[tv][3])}; } }
.LBB0_627:
	ds_read_b128 v[134:137], v121
	ds_read_b128 v[150:153], v132 offset:55296
	ds_read_b128 v[170:173], v123
	ds_read_b128 v[138:141], v121 offset:64
	ds_read_b128 v[154:157], v132 offset:55360
	ds_read_b128 v[174:177], v123 offset:64
	ds_read_b128 v[142:145], v121 offset:128
	ds_read_b128 v[158:161], v132 offset:55424
	ds_read_b128 v[178:181], v123 offset:128
	ds_read_b128 v[146:149], v121 offset:192
	ds_read_b128 v[162:165], v132 offset:55488
	ds_read_b128 v[182:185], v123 offset:192
	v_add_u32_e32 v133, v110, v105
	s_waitcnt lgkmcnt(10)
	v_mfma_f32_16x16x32_bf16 v[222:225], v[134:137], v[150:153], 0
	s_waitcnt lgkmcnt(9)
	v_mfma_f32_16x16x32_bf16 v[226:229], v[170:173], v[150:153], 0
	ds_read_b128 v[194:197], v133
	ds_read_b128 v[186:189], v122
	ds_read_b128 v[202:205], v124
	ds_read_b128 v[198:201], v133 offset:64
	ds_read_b128 v[190:193], v122 offset:64
	ds_read_b128 v[206:209], v124 offset:64
	s_add_i32 s18, s31, -1
	s_and_b64 s[16:17], s[12:13], exec
	s_cselect_b32 s16, s34, s18
	s_lshl_b32 s16, s16, 6
	s_add_i32 s16, s16, s8
	s_ashr_i32 s17, s16, 31
	v_or_b32_e32 v210, s16, v86
	v_mov_b32_e32 v211, s17
	v_lshlrev_b64 v[212:213], 12, v[210:211]
	v_lshl_add_u64 v[214:215], s[14:15], 0, v[212:213]
	v_lshl_add_u64 v[218:219], v[98:99], 1, v[214:215]
	v_lshl_add_u64 v[220:221], v[100:101], 1, v[214:215]
	v_lshl_add_u64 v[220:221], v[220:221], 0, 32
	s_waitcnt lgkmcnt(13)
	v_mfma_f32_16x16x32_bf16 v[222:225], v[138:141], v[154:157], v[222:225]
	s_waitcnt lgkmcnt(12)
	v_mfma_f32_16x16x32_bf16 v[226:229], v[174:177], v[154:157], v[226:229]
	s_waitcnt lgkmcnt(10)
	v_mfma_f32_16x16x32_bf16 v[222:225], v[142:145], v[158:161], v[222:225]
	s_waitcnt lgkmcnt(9)
	v_mfma_f32_16x16x32_bf16 v[226:229], v[178:181], v[158:161], v[226:229]
	s_waitcnt lgkmcnt(7)
	v_mfma_f32_16x16x32_bf16 v[222:225], v[146:149], v[162:165], v[222:225]
	s_waitcnt lgkmcnt(6)
	v_mfma_f32_16x16x32_bf16 v[226:229], v[182:185], v[162:165], v[226:229]
	v_add_u32_e32 v136, 0x18800, v129
	ds_read_b128 v[136:139], v136
	ds_read_b128 v[132:135], v125
	v_add_u32_e32 v148, v112, v105
	ds_read_b128 v[140:143], v148
	ds_read_b128 v[144:147], v125 offset:64
	ds_read_b128 v[170:173], v148 offset:64
	ds_read_b128 v[174:177], v126
	ds_read_b128 v[178:181], v126 offset:64
	ds_read_b128 v[182:185], v127
	s_waitcnt lgkmcnt(12)
	v_mfma_f32_16x16x32_bf16 v[222:225], v[194:197], v[186:189], v[222:225]
	s_waitcnt lgkmcnt(11)
	v_mfma_f32_16x16x32_bf16 v[226:229], v[202:205], v[186:189], v[226:229]
	s_waitcnt lgkmcnt(9)
	v_mfma_f32_16x16x32_bf16 v[222:225], v[198:201], v[190:193], v[222:225]
	s_waitcnt lgkmcnt(8)
	v_mfma_f32_16x16x32_bf16 v[226:229], v[206:209], v[190:193], v[226:229]
	ds_read_b128 v[186:189], v127 offset:64
	ds_read_b128 v[190:193], v128
	ds_read_b128 v[194:197], v128 offset:64
	s_add_i32 s30, s30, 2
	s_add_i32 s31, s31, -2
	s_waitcnt lgkmcnt(10)
	v_pk_mul_f32 v[80:81], v[80:81], v[138:139]
	v_pk_mul_f32 v[78:79], v[78:79], v[136:137]
	v_pk_mul_f32 v[76:77], v[76:77], v[138:139]
	v_pk_mul_f32 v[74:75], v[74:75], v[136:137]
	v_pk_mul_f32 v[72:73], v[72:73], v[138:139]
	v_pk_mul_f32 v[70:71], v[70:71], v[136:137]
	v_mul_f32_e64 v68, v68, v138
	v_mul_f32_e64 v69, v69, v139
	v_pk_mul_f32 v[66:67], v[66:67], v[136:137]
	v_cvt_pk_bf16_f32 v230, v222, v223
	v_cvt_pk_bf16_f32 v231, v224, v225
	global_store_dwordx2 v[218:219], v[230:231], off
	s_nop 1
	v_cvt_pk_bf16_f32 v232, v226, v227
	v_cvt_pk_bf16_f32 v233, v228, v229
	global_store_dwordx2 v[220:221], v[232:233], off
	s_nop 1
	s_branch .Lmy_so_tail
